# S5 Toeplitz loops regenerated: 4 tap reads + u fragment issued together, out-of-range taps read a zero LDS slot (address select) instead of masking data
# speedup vs baseline: 1.0038x; 1.0038x over previous
.LBB0_432:
	s_or_b64 exec, exec, s[34:35]
	v_readlane_b32 s0, v254, 30
	v_readlane_b32 s1, v254, 31
	s_andn2_b64 vcc, exec, s[0:1]
	s_waitcnt lgkmcnt(0)
	s_barrier
	v_mov_b32_e32 v214, 0
	v_mov_b32_e32 v215, 0
	v_mov_b32_e32 v216, 0
	v_mov_b32_e32 v217, 0
	v_mov_b32_e32 v218, 0xf000
	v_mov_b32_e32 v246, 0xe000
	ds_write_b128 v218, v[214:217]
	s_cbranch_vccnz .LBB0_764
	v_readlane_b32 s36, v252, 34
	s_lshl_b32 s60, s58, 8
	s_lshl_b32 s0, s58, 5
	v_readlane_b32 s42, v252, 40
	v_readlane_b32 s43, v252, 41
	s_lshl_b32 s29, s58, 2
	v_writelane_b32 v253, s0, 15
	s_lshl_b64 s[0:1], s[60:61], 2
	s_mov_b64 s[6:7], s[42:43]
	s_add_u32 s0, s6, s0
	v_writelane_b32 v251, s0, 6
	s_addc_u32 s0, s7, s1
	v_readlane_b32 s6, v254, 32
	v_readlane_b32 s64, v253, 4
	v_readlane_b32 s7, v254, 33
	v_readlane_b32 s37, v252, 35
	v_readlane_b32 s38, v252, 36
	v_readlane_b32 s39, v252, 37
	v_readlane_b32 s40, v252, 38
	v_readlane_b32 s41, v252, 39
	v_readlane_b32 s44, v252, 42
	v_readlane_b32 s45, v252, 43
	v_readlane_b32 s46, v252, 44
	v_readlane_b32 s47, v252, 45
	v_readlane_b32 s48, v252, 46
	v_readlane_b32 s49, v252, 47
	v_readlane_b32 s50, v252, 48
	v_readlane_b32 s51, v252, 49
	v_writelane_b32 v251, s0, 7
	s_branch .LBB0_436

.LBB0_565:
	v_add_u32_e32 v234, 12, v0
	v_cndmask_b32_e64 v230, v234, v2, s[38:39]
	v_max_i32_e32 v214, 0, v230
	v_lshl_add_u32 v214, v214, 9, v91
	v_add_u32_e32 v235, 8, v0
	v_add_u32_e32 v239, 4, v2
	v_cndmask_b32_e64 v231, v235, v239, s[38:39]
	v_max_i32_e32 v218, 0, v231
	v_lshl_add_u32 v218, v218, 9, v91
	v_add_u32_e32 v236, 4, v0
	v_add_u32_e32 v240, 8, v2
	v_cndmask_b32_e64 v232, v236, v240, s[38:39]
	v_max_i32_e32 v222, 0, v232
	v_lshl_add_u32 v222, v222, 9, v91
	v_add_u32_e32 v241, 12, v2
	v_cndmask_b32_e64 v233, v0, v241, s[38:39]
	v_max_i32_e32 v226, 0, v233
	v_lshl_add_u32 v226, v226, 9, v91
	v_cmp_lt_i32_e64 s[98:99], -1, v230
	v_cmp_lt_i32_e64 s[100:101], -1, v231
	v_cmp_lt_i32_e64 vcc, -1, v232
	v_cndmask_b32_e64 v214, v246, v214, s[98:99]
	v_cmp_lt_i32_e64 s[98:99], -1, v233
	v_cndmask_b32_e64 v218, v246, v218, s[100:101]
	v_cndmask_b32_e64 v222, v246, v222, vcc
	s_nop 0
	v_cndmask_b32_e64 v226, v246, v226, s[98:99]
	ds_read_b128 v[214:217], v214 offset:4096
	ds_read_b128 v[218:221], v218 offset:4096
	ds_read_b128 v[222:225], v222 offset:4096
	ds_read_b128 v[226:229], v226 offset:4096
	ds_read_b128 v[20:23], v3
	v_add_u32_e32 v0, 2, v0
	v_add_u32_e32 v2, -2, v2
	v_add_u32_e32 v3, 64, v3
	s_add_i32 s36, s36, 1
	s_cmp_lt_i32 s36, s33
	s_waitcnt lgkmcnt(0)
	v_mfma_f32_16x16x32_bf16 v[16:19], v[214:217], v[20:23], v[16:19]
	v_mfma_f32_16x16x32_bf16 v[12:15], v[218:221], v[20:23], v[12:15]
	v_mfma_f32_16x16x32_bf16 v[8:11], v[222:225], v[20:23], v[8:11]
	v_mfma_f32_16x16x32_bf16 v[4:7], v[226:229], v[20:23], v[4:7]
	s_cbranch_scc1 .LBB0_565
	s_cmp_eq_u32 s3, 1
	s_cselect_b64 s[44:45], -1, 0
	s_cmp_lg_u32 s3, 1
	s_cbranch_scc1 .LBB0_582

.LBB0_569:
	v_add_u32_e32 v234, 12, v0
	v_add_u32_e32 v238, -12, v2
	v_cndmask_b32_e64 v230, v234, v238, s[38:39]
	v_max_i32_e32 v214, 0, v230
	v_lshl_add_u32 v214, v214, 9, v91
	v_add_u32_e32 v235, 8, v0
	v_add_u32_e32 v239, -8, v2
	v_cndmask_b32_e64 v231, v235, v239, s[38:39]
	v_max_i32_e32 v218, 0, v231
	v_lshl_add_u32 v218, v218, 9, v91
	v_add_u32_e32 v236, 4, v0
	v_add_u32_e32 v240, -4, v2
	v_cndmask_b32_e64 v232, v236, v240, s[38:39]
	v_max_i32_e32 v222, 0, v232
	v_lshl_add_u32 v222, v222, 9, v91
	v_cndmask_b32_e64 v233, v0, v2, s[38:39]
	v_max_i32_e32 v226, 0, v233
	v_lshl_add_u32 v226, v226, 9, v91
	v_cmp_lt_i32_e64 s[98:99], -1, v230
	v_cmp_lt_i32_e64 s[100:101], -1, v231
	v_cmp_lt_i32_e64 vcc, -1, v232
	v_cndmask_b32_e64 v214, v246, v214, s[98:99]
	v_cmp_lt_i32_e64 s[98:99], -1, v233
	v_cndmask_b32_e64 v218, v246, v218, s[100:101]
	v_cndmask_b32_e64 v222, v246, v222, vcc
	s_nop 0
	v_cndmask_b32_e64 v226, v246, v226, s[98:99]
	ds_read_b128 v[214:217], v214 offset:4096
	ds_read_b128 v[218:221], v218 offset:4096
	ds_read_b128 v[222:225], v222 offset:4096
	ds_read_b128 v[226:229], v226 offset:4096
	ds_read_b128 v[36:39], v3
	v_add_u32_e32 v0, 2, v0
	v_add_u32_e32 v2, -2, v2
	v_add_u32_e32 v3, 64, v3
	s_add_i32 s36, s36, 1
	s_cmp_lt_i32 s36, s33
	s_waitcnt lgkmcnt(0)
	v_mfma_f32_16x16x32_bf16 v[32:35], v[214:217], v[36:39], v[32:35]
	v_mfma_f32_16x16x32_bf16 v[28:31], v[218:221], v[36:39], v[28:31]
	v_mfma_f32_16x16x32_bf16 v[24:27], v[222:225], v[36:39], v[24:27]
	v_mfma_f32_16x16x32_bf16 v[20:23], v[226:229], v[36:39], v[20:23]
	s_cbranch_scc1 .LBB0_569
	s_branch .LBB0_571

.LBB0_574:
	v_add_u32_e32 v234, 12, v0
	v_add_u32_e32 v238, -12, v2
	v_cndmask_b32_e64 v230, v234, v238, s[38:39]
	v_max_i32_e32 v214, 0, v230
	v_lshl_add_u32 v214, v214, 9, v91
	v_add_u32_e32 v235, 8, v0
	v_add_u32_e32 v239, -8, v2
	v_cndmask_b32_e64 v231, v235, v239, s[38:39]
	v_max_i32_e32 v218, 0, v231
	v_lshl_add_u32 v218, v218, 9, v91
	v_add_u32_e32 v236, 4, v0
	v_add_u32_e32 v240, -4, v2
	v_cndmask_b32_e64 v232, v236, v240, s[38:39]
	v_max_i32_e32 v222, 0, v232
	v_lshl_add_u32 v222, v222, 9, v91
	v_cndmask_b32_e64 v233, v0, v2, s[38:39]
	v_max_i32_e32 v226, 0, v233
	v_lshl_add_u32 v226, v226, 9, v91
	v_cmp_lt_i32_e64 s[98:99], -1, v230
	v_cmp_lt_i32_e64 s[100:101], -1, v231
	v_cmp_lt_i32_e64 vcc, -1, v232
	v_cndmask_b32_e64 v214, v246, v214, s[98:99]
	v_cmp_lt_i32_e64 s[98:99], -1, v233
	v_cndmask_b32_e64 v218, v246, v218, s[100:101]
	v_cndmask_b32_e64 v222, v246, v222, vcc
	s_nop 0
	v_cndmask_b32_e64 v226, v246, v226, s[98:99]
	ds_read_b128 v[214:217], v214 offset:4096
	ds_read_b128 v[218:221], v218 offset:4096
	ds_read_b128 v[222:225], v222 offset:4096
	ds_read_b128 v[226:229], v226 offset:4096
	ds_read_b128 v[68:71], v3
	v_add_u32_e32 v0, 2, v0
	v_add_u32_e32 v2, -2, v2
	v_add_u32_e32 v3, 64, v3
	s_add_i32 s36, s36, 1
	s_cmp_lt_i32 s36, s33
	s_waitcnt lgkmcnt(0)
	v_mfma_f32_16x16x32_bf16 v[56:59], v[214:217], v[68:71], v[56:59]
	v_mfma_f32_16x16x32_bf16 v[52:55], v[218:221], v[68:71], v[52:55]
	v_mfma_f32_16x16x32_bf16 v[44:47], v[222:225], v[68:71], v[44:47]
	v_mfma_f32_16x16x32_bf16 v[36:39], v[226:229], v[68:71], v[36:39]
	s_cbranch_scc1 .LBB0_574
	s_branch .LBB0_576

.LBB0_579:
	v_add_u32_e32 v234, 12, v0
	v_add_u32_e32 v238, -12, v2
	v_cndmask_b32_e64 v230, v234, v238, s[38:39]
	v_max_i32_e32 v214, 0, v230
	v_lshl_add_u32 v214, v214, 9, v91
	v_add_u32_e32 v235, 8, v0
	v_add_u32_e32 v239, -8, v2
	v_cndmask_b32_e64 v231, v235, v239, s[38:39]
	v_max_i32_e32 v218, 0, v231
	v_lshl_add_u32 v218, v218, 9, v91
	v_add_u32_e32 v236, 4, v0
	v_add_u32_e32 v240, -4, v2
	v_cndmask_b32_e64 v232, v236, v240, s[38:39]
	v_max_i32_e32 v222, 0, v232
	v_lshl_add_u32 v222, v222, 9, v91
	v_cndmask_b32_e64 v233, v0, v2, s[38:39]
	v_max_i32_e32 v226, 0, v233
	v_lshl_add_u32 v226, v226, 9, v91
	v_cmp_lt_i32_e64 s[98:99], -1, v230
	v_cmp_lt_i32_e64 s[100:101], -1, v231
	v_cmp_lt_i32_e64 vcc, -1, v232
	v_cndmask_b32_e64 v214, v246, v214, s[98:99]
	v_cmp_lt_i32_e64 s[98:99], -1, v233
	v_cndmask_b32_e64 v218, v246, v218, s[100:101]
	v_cndmask_b32_e64 v222, v246, v222, vcc
	s_nop 0
	v_cndmask_b32_e64 v226, v246, v226, s[98:99]
	ds_read_b128 v[214:217], v214 offset:4096
	ds_read_b128 v[218:221], v218 offset:4096
	ds_read_b128 v[222:225], v222 offset:4096
	ds_read_b128 v[226:229], v226 offset:4096
	ds_read_b128 v[84:87], v3
	v_add_u32_e32 v0, 2, v0
	v_add_u32_e32 v2, -2, v2
	v_add_u32_e32 v3, 64, v3
	s_add_i32 s33, s33, 1
	s_cmp_lt_i32 s33, s3
	s_waitcnt lgkmcnt(0)
	v_mfma_f32_16x16x32_bf16 v[80:83], v[214:217], v[84:87], v[80:83]
	v_mfma_f32_16x16x32_bf16 v[76:79], v[218:221], v[84:87], v[76:79]
	v_mfma_f32_16x16x32_bf16 v[72:75], v[222:225], v[84:87], v[72:75]
	v_mfma_f32_16x16x32_bf16 v[68:71], v[226:229], v[84:87], v[68:71]
	s_cbranch_scc1 .LBB0_579
	s_branch .LBB0_585

.LBB0_588:
	v_add_u32_e32 v234, 12, v0
	v_cndmask_b32_e64 v230, v234, v2, s[38:39]
	v_max_i32_e32 v214, 0, v230
	v_lshl_add_u32 v214, v214, 9, v91
	v_add_u32_e32 v235, 8, v0
	v_add_u32_e32 v239, 4, v2
	v_cndmask_b32_e64 v231, v235, v239, s[38:39]
	v_max_i32_e32 v218, 0, v231
	v_lshl_add_u32 v218, v218, 9, v91
	v_add_u32_e32 v236, 4, v0
	v_add_u32_e32 v240, 8, v2
	v_cndmask_b32_e64 v232, v236, v240, s[38:39]
	v_max_i32_e32 v222, 0, v232
	v_lshl_add_u32 v222, v222, 9, v91
	v_add_u32_e32 v241, 12, v2
	v_cndmask_b32_e64 v233, v0, v241, s[38:39]
	v_max_i32_e32 v226, 0, v233
	v_lshl_add_u32 v226, v226, 9, v91
	v_cmp_lt_i32_e64 s[98:99], -1, v230
	v_cmp_lt_i32_e64 s[100:101], -1, v231
	v_cmp_lt_i32_e64 vcc, -1, v232
	v_cndmask_b32_e64 v214, v246, v214, s[98:99]
	v_cmp_lt_i32_e64 s[98:99], -1, v233
	v_cndmask_b32_e64 v218, v246, v218, s[100:101]
	v_cndmask_b32_e64 v222, v246, v222, vcc
	s_nop 0
	v_cndmask_b32_e64 v226, v246, v226, s[98:99]
	ds_read_b128 v[214:217], v214 offset:4096
	ds_read_b128 v[218:221], v218 offset:4096
	ds_read_b128 v[222:225], v222 offset:4096
	ds_read_b128 v[226:229], v226 offset:4096
	ds_read_b128 v[40:43], v3
	v_add_u32_e32 v0, 2, v0
	v_add_u32_e32 v2, -2, v2
	v_add_u32_e32 v3, 64, v3
	s_add_i32 s33, s33, 1
	s_cmp_lt_i32 s33, s3
	s_waitcnt lgkmcnt(0)
	v_mfma_f32_16x16x32_bf16 v[16:19], v[214:217], v[40:43], v[16:19]
	v_mfma_f32_16x16x32_bf16 v[12:15], v[218:221], v[40:43], v[12:15]
	v_mfma_f32_16x16x32_bf16 v[8:11], v[222:225], v[40:43], v[8:11]
	v_mfma_f32_16x16x32_bf16 v[4:7], v[226:229], v[40:43], v[4:7]
	s_cbranch_scc1 .LBB0_588

.LBB0_592:
	v_add_u32_e32 v234, 12, v0
	v_add_u32_e32 v238, -12, v2
	v_cndmask_b32_e64 v230, v234, v238, s[38:39]
	v_max_i32_e32 v214, 0, v230
	v_lshl_add_u32 v214, v214, 9, v91
	v_add_u32_e32 v235, 8, v0
	v_add_u32_e32 v239, -8, v2
	v_cndmask_b32_e64 v231, v235, v239, s[38:39]
	v_max_i32_e32 v218, 0, v231
	v_lshl_add_u32 v218, v218, 9, v91
	v_add_u32_e32 v236, 4, v0
	v_add_u32_e32 v240, -4, v2
	v_cndmask_b32_e64 v232, v236, v240, s[38:39]
	v_max_i32_e32 v222, 0, v232
	v_lshl_add_u32 v222, v222, 9, v91
	v_cndmask_b32_e64 v233, v0, v2, s[38:39]
	v_max_i32_e32 v226, 0, v233
	v_lshl_add_u32 v226, v226, 9, v91
	v_cmp_lt_i32_e64 s[98:99], -1, v230
	v_cmp_lt_i32_e64 s[100:101], -1, v231
	v_cmp_lt_i32_e64 vcc, -1, v232
	v_cndmask_b32_e64 v214, v246, v214, s[98:99]
	v_cmp_lt_i32_e64 s[98:99], -1, v233
	v_cndmask_b32_e64 v218, v246, v218, s[100:101]
	v_cndmask_b32_e64 v222, v246, v222, vcc
	s_nop 0
	v_cndmask_b32_e64 v226, v246, v226, s[98:99]
	ds_read_b128 v[214:217], v214 offset:4096
	ds_read_b128 v[218:221], v218 offset:4096
	ds_read_b128 v[222:225], v222 offset:4096
	ds_read_b128 v[226:229], v226 offset:4096
	ds_read_b128 v[40:43], v3
	v_add_u32_e32 v0, 2, v0
	v_add_u32_e32 v2, -2, v2
	v_add_u32_e32 v3, 64, v3
	s_add_i32 s33, s33, 1
	s_cmp_lt_i32 s33, s3
	s_waitcnt lgkmcnt(0)
	v_mfma_f32_16x16x32_bf16 v[32:35], v[214:217], v[40:43], v[32:35]
	v_mfma_f32_16x16x32_bf16 v[28:31], v[218:221], v[40:43], v[28:31]
	v_mfma_f32_16x16x32_bf16 v[24:27], v[222:225], v[40:43], v[24:27]
	v_mfma_f32_16x16x32_bf16 v[20:23], v[226:229], v[40:43], v[20:23]
	s_cbranch_scc1 .LBB0_592

.LBB0_596:
	v_add_u32_e32 v234, 12, v0
	v_add_u32_e32 v238, -12, v2
	v_cndmask_b32_e64 v230, v234, v238, s[38:39]
	v_max_i32_e32 v214, 0, v230
	v_lshl_add_u32 v214, v214, 9, v91
	v_add_u32_e32 v235, 8, v0
	v_add_u32_e32 v239, -8, v2
	v_cndmask_b32_e64 v231, v235, v239, s[38:39]
	v_max_i32_e32 v218, 0, v231
	v_lshl_add_u32 v218, v218, 9, v91
	v_add_u32_e32 v236, 4, v0
	v_add_u32_e32 v240, -4, v2
	v_cndmask_b32_e64 v232, v236, v240, s[38:39]
	v_max_i32_e32 v222, 0, v232
	v_lshl_add_u32 v222, v222, 9, v91
	v_cndmask_b32_e64 v233, v0, v2, s[38:39]
	v_max_i32_e32 v226, 0, v233
	v_lshl_add_u32 v226, v226, 9, v91
	v_cmp_lt_i32_e64 s[98:99], -1, v230
	v_cmp_lt_i32_e64 s[100:101], -1, v231
	v_cmp_lt_i32_e64 vcc, -1, v232
	v_cndmask_b32_e64 v214, v246, v214, s[98:99]
	v_cmp_lt_i32_e64 s[98:99], -1, v233
	v_cndmask_b32_e64 v218, v246, v218, s[100:101]
	v_cndmask_b32_e64 v222, v246, v222, vcc
	s_nop 0
	v_cndmask_b32_e64 v226, v246, v226, s[98:99]
	ds_read_b128 v[214:217], v214 offset:4096
	ds_read_b128 v[218:221], v218 offset:4096
	ds_read_b128 v[222:225], v222 offset:4096
	ds_read_b128 v[226:229], v226 offset:4096
	ds_read_b128 v[40:43], v3
	v_add_u32_e32 v0, 2, v0
	v_add_u32_e32 v2, -2, v2
	v_add_u32_e32 v3, 64, v3
	s_add_i32 s33, s33, 1
	s_cmp_lt_i32 s33, s3
	s_waitcnt lgkmcnt(0)
	v_mfma_f32_16x16x32_bf16 v[56:59], v[214:217], v[40:43], v[56:59]
	v_mfma_f32_16x16x32_bf16 v[52:55], v[218:221], v[40:43], v[52:55]
	v_mfma_f32_16x16x32_bf16 v[44:47], v[222:225], v[40:43], v[44:47]
	v_mfma_f32_16x16x32_bf16 v[36:39], v[226:229], v[40:43], v[36:39]
	s_cbranch_scc1 .LBB0_596

.LBB0_600:
	v_add_u32_e32 v234, 12, v0
	v_add_u32_e32 v238, -12, v2
	v_cndmask_b32_e64 v230, v234, v238, s[38:39]
	v_max_i32_e32 v214, 0, v230
	v_lshl_add_u32 v214, v214, 9, v91
	v_add_u32_e32 v235, 8, v0
	v_add_u32_e32 v239, -8, v2
	v_cndmask_b32_e64 v231, v235, v239, s[38:39]
	v_max_i32_e32 v218, 0, v231
	v_lshl_add_u32 v218, v218, 9, v91
	v_add_u32_e32 v236, 4, v0
	v_add_u32_e32 v240, -4, v2
	v_cndmask_b32_e64 v232, v236, v240, s[38:39]
	v_max_i32_e32 v222, 0, v232
	v_lshl_add_u32 v222, v222, 9, v91
	v_cndmask_b32_e64 v233, v0, v2, s[38:39]
	v_max_i32_e32 v226, 0, v233
	v_lshl_add_u32 v226, v226, 9, v91
	v_cmp_lt_i32_e64 s[98:99], -1, v230
	v_cmp_lt_i32_e64 s[100:101], -1, v231
	v_cmp_lt_i32_e64 vcc, -1, v232
	v_cndmask_b32_e64 v214, v246, v214, s[98:99]
	v_cmp_lt_i32_e64 s[98:99], -1, v233
	v_cndmask_b32_e64 v218, v246, v218, s[100:101]
	v_cndmask_b32_e64 v222, v246, v222, vcc
	s_nop 0
	v_cndmask_b32_e64 v226, v246, v226, s[98:99]
	ds_read_b128 v[214:217], v214 offset:4096
	ds_read_b128 v[218:221], v218 offset:4096
	ds_read_b128 v[222:225], v222 offset:4096
	ds_read_b128 v[226:229], v226 offset:4096
	ds_read_b128 v[40:43], v3
	v_add_u32_e32 v0, 2, v0
	v_add_u32_e32 v2, -2, v2
	v_add_u32_e32 v3, 64, v3
	s_add_i32 s3, s3, 1
	s_cmp_lt_i32 s3, s2
	s_waitcnt lgkmcnt(0)
	v_mfma_f32_16x16x32_bf16 v[80:83], v[214:217], v[40:43], v[80:83]
	v_mfma_f32_16x16x32_bf16 v[76:79], v[218:221], v[40:43], v[76:79]
	v_mfma_f32_16x16x32_bf16 v[72:75], v[222:225], v[40:43], v[72:75]
	v_mfma_f32_16x16x32_bf16 v[68:71], v[226:229], v[40:43], v[68:71]
	s_cbranch_scc1 .LBB0_600

.LBB0_721:
	v_add_u32_e32 v234, 12, v0
	v_cndmask_b32_e64 v230, v234, v2, vcc
	v_max_i32_e32 v214, 0, v230
	v_lshl_add_u32 v214, v214, 9, v89
	v_add_u32_e32 v235, 8, v0
	v_add_u32_e32 v239, 4, v2
	v_cndmask_b32_e64 v231, v235, v239, vcc
	v_max_i32_e32 v218, 0, v231
	v_lshl_add_u32 v218, v218, 9, v89
	v_add_u32_e32 v236, 4, v0
	v_add_u32_e32 v240, 8, v2
	v_cndmask_b32_e64 v232, v236, v240, vcc
	v_max_i32_e32 v222, 0, v232
	v_lshl_add_u32 v222, v222, 9, v89
	v_add_u32_e32 v241, 12, v2
	v_cndmask_b32_e64 v233, v0, v241, vcc
	v_max_i32_e32 v226, 0, v233
	v_lshl_add_u32 v226, v226, 9, v89
	v_cmp_lt_i32_e64 s[98:99], -1, v230
	v_cmp_lt_i32_e64 s[100:101], -1, v231
	v_cmp_lt_i32_e64 s[38:39], -1, v232
	v_cndmask_b32_e64 v214, v246, v214, s[98:99]
	v_cmp_lt_i32_e64 s[98:99], -1, v233
	v_cndmask_b32_e64 v218, v246, v218, s[100:101]
	v_cndmask_b32_e64 v222, v246, v222, s[38:39]
	s_nop 0
	v_cndmask_b32_e64 v226, v246, v226, s[98:99]
	ds_read_b128 v[214:217], v214 offset:4096
	ds_read_b128 v[218:221], v218 offset:4096
	ds_read_b128 v[222:225], v222 offset:4096
	ds_read_b128 v[226:229], v226 offset:4096
	ds_read_b128 v[20:23], v3
	v_add_u32_e32 v0, 2, v0
	v_add_u32_e32 v2, -2, v2
	v_add_u32_e32 v3, 64, v3
	s_add_i32 s33, s33, 1
	s_cmp_lt_i32 s33, s19
	s_waitcnt lgkmcnt(0)
	v_mfma_f32_16x16x32_bf16 v[16:19], v[214:217], v[20:23], v[16:19]
	v_mfma_f32_16x16x32_bf16 v[12:15], v[218:221], v[20:23], v[12:15]
	v_mfma_f32_16x16x32_bf16 v[8:11], v[222:225], v[20:23], v[8:11]
	v_mfma_f32_16x16x32_bf16 v[4:7], v[226:229], v[20:23], v[4:7]
	s_cbranch_scc1 .LBB0_721
	s_branch .LBB0_723

.LBB0_725:
	v_add_u32_e32 v234, 12, v0
	v_add_u32_e32 v238, -12, v2
	v_cndmask_b32_e64 v230, v234, v238, vcc
	v_max_i32_e32 v214, 0, v230
	v_lshl_add_u32 v214, v214, 9, v89
	v_add_u32_e32 v235, 8, v0
	v_add_u32_e32 v239, -8, v2
	v_cndmask_b32_e64 v231, v235, v239, vcc
	v_max_i32_e32 v218, 0, v231
	v_lshl_add_u32 v218, v218, 9, v89
	v_add_u32_e32 v236, 4, v0
	v_add_u32_e32 v240, -4, v2
	v_cndmask_b32_e64 v232, v236, v240, vcc
	v_max_i32_e32 v222, 0, v232
	v_lshl_add_u32 v222, v222, 9, v89
	v_cndmask_b32_e64 v233, v0, v2, vcc
	v_max_i32_e32 v226, 0, v233
	v_lshl_add_u32 v226, v226, 9, v89
	v_cmp_lt_i32_e64 s[98:99], -1, v230
	v_cmp_lt_i32_e64 s[100:101], -1, v231
	v_cmp_lt_i32_e64 s[38:39], -1, v232
	v_cndmask_b32_e64 v214, v246, v214, s[98:99]
	v_cmp_lt_i32_e64 s[98:99], -1, v233
	v_cndmask_b32_e64 v218, v246, v218, s[100:101]
	v_cndmask_b32_e64 v222, v246, v222, s[38:39]
	s_nop 0
	v_cndmask_b32_e64 v226, v246, v226, s[98:99]
	ds_read_b128 v[214:217], v214 offset:4096
	ds_read_b128 v[218:221], v218 offset:4096
	ds_read_b128 v[222:225], v222 offset:4096
	ds_read_b128 v[226:229], v226 offset:4096
	ds_read_b128 v[36:39], v3
	v_add_u32_e32 v0, 2, v0
	v_add_u32_e32 v2, -2, v2
	v_add_u32_e32 v3, 64, v3
	s_add_i32 s37, s37, 1
	s_cmp_lt_i32 s37, s36
	s_waitcnt lgkmcnt(0)
	v_mfma_f32_16x16x32_bf16 v[32:35], v[214:217], v[36:39], v[32:35]
	v_mfma_f32_16x16x32_bf16 v[28:31], v[218:221], v[36:39], v[28:31]
	v_mfma_f32_16x16x32_bf16 v[24:27], v[222:225], v[36:39], v[24:27]
	v_mfma_f32_16x16x32_bf16 v[20:23], v[226:229], v[36:39], v[20:23]
	s_cbranch_scc1 .LBB0_725
	s_branch .LBB0_727

.LBB0_729:
	v_add_u32_e32 v234, 12, v0
	v_add_u32_e32 v238, -12, v2
	v_cndmask_b32_e64 v230, v234, v238, vcc
	v_max_i32_e32 v214, 0, v230
	v_lshl_add_u32 v214, v214, 9, v89
	v_add_u32_e32 v235, 8, v0
	v_add_u32_e32 v239, -8, v2
	v_cndmask_b32_e64 v231, v235, v239, vcc
	v_max_i32_e32 v218, 0, v231
	v_lshl_add_u32 v218, v218, 9, v89
	v_add_u32_e32 v236, 4, v0
	v_add_u32_e32 v240, -4, v2
	v_cndmask_b32_e64 v232, v236, v240, vcc
	v_max_i32_e32 v222, 0, v232
	v_lshl_add_u32 v222, v222, 9, v89
	v_cndmask_b32_e64 v233, v0, v2, vcc
	v_max_i32_e32 v226, 0, v233
	v_lshl_add_u32 v226, v226, 9, v89
	v_cmp_lt_i32_e64 s[98:99], -1, v230
	v_cmp_lt_i32_e64 s[100:101], -1, v231
	v_cmp_lt_i32_e64 s[38:39], -1, v232
	v_cndmask_b32_e64 v214, v246, v214, s[98:99]
	v_cmp_lt_i32_e64 s[98:99], -1, v233
	v_cndmask_b32_e64 v218, v246, v218, s[100:101]
	v_cndmask_b32_e64 v222, v246, v222, s[38:39]
	s_nop 0
	v_cndmask_b32_e64 v226, v246, v226, s[98:99]
	ds_read_b128 v[214:217], v214 offset:4096
	ds_read_b128 v[218:221], v218 offset:4096
	ds_read_b128 v[222:225], v222 offset:4096
	ds_read_b128 v[226:229], v226 offset:4096
	ds_read_b128 v[68:71], v3
	v_add_u32_e32 v0, 2, v0
	v_add_u32_e32 v2, -2, v2
	v_add_u32_e32 v3, 64, v3
	s_add_i32 s42, s42, 1
	s_cmp_lt_i32 s42, s40
	s_waitcnt lgkmcnt(0)
	v_mfma_f32_16x16x32_bf16 v[48:51], v[214:217], v[68:71], v[48:51]
	v_mfma_f32_16x16x32_bf16 v[44:47], v[218:221], v[68:71], v[44:47]
	v_mfma_f32_16x16x32_bf16 v[40:43], v[222:225], v[68:71], v[40:43]
	v_mfma_f32_16x16x32_bf16 v[36:39], v[226:229], v[68:71], v[36:39]
	s_cbranch_scc1 .LBB0_729
	s_branch .LBB0_731

.LBB0_733:
	v_add_u32_e32 v234, 12, v0
	v_add_u32_e32 v238, -12, v2
	v_cndmask_b32_e64 v230, v234, v238, vcc
	v_max_i32_e32 v214, 0, v230
	v_lshl_add_u32 v214, v214, 9, v89
	v_add_u32_e32 v235, 8, v0
	v_add_u32_e32 v239, -8, v2
	v_cndmask_b32_e64 v231, v235, v239, vcc
	v_max_i32_e32 v218, 0, v231
	v_lshl_add_u32 v218, v218, 9, v89
	v_add_u32_e32 v236, 4, v0
	v_add_u32_e32 v240, -4, v2
	v_cndmask_b32_e64 v232, v236, v240, vcc
	v_max_i32_e32 v222, 0, v232
	v_lshl_add_u32 v222, v222, 9, v89
	v_cndmask_b32_e64 v233, v0, v2, vcc
	v_max_i32_e32 v226, 0, v233
	v_lshl_add_u32 v226, v226, 9, v89
	v_cmp_lt_i32_e64 s[98:99], -1, v230
	v_cmp_lt_i32_e64 s[100:101], -1, v231
	v_cmp_lt_i32_e64 s[38:39], -1, v232
	v_cndmask_b32_e64 v214, v246, v214, s[98:99]
	v_cmp_lt_i32_e64 s[98:99], -1, v233
	v_cndmask_b32_e64 v218, v246, v218, s[100:101]
	v_cndmask_b32_e64 v222, v246, v222, s[38:39]
	s_nop 0
	v_cndmask_b32_e64 v226, v246, v226, s[98:99]
	ds_read_b128 v[214:217], v214 offset:4096
	ds_read_b128 v[218:221], v218 offset:4096
	ds_read_b128 v[222:225], v222 offset:4096
	ds_read_b128 v[226:229], v226 offset:4096
	ds_read_b128 v[84:87], v3
	v_add_u32_e32 v0, 2, v0
	v_add_u32_e32 v2, -2, v2
	v_add_u32_e32 v3, 64, v3
	s_add_i32 s43, s43, 1
	s_cmp_lt_i32 s43, s42
	s_waitcnt lgkmcnt(0)
	v_mfma_f32_16x16x32_bf16 v[80:83], v[214:217], v[84:87], v[80:83]
	v_mfma_f32_16x16x32_bf16 v[76:79], v[218:221], v[84:87], v[76:79]
	v_mfma_f32_16x16x32_bf16 v[72:75], v[222:225], v[84:87], v[72:75]
	v_mfma_f32_16x16x32_bf16 v[68:71], v[226:229], v[84:87], v[68:71]
	s_cbranch_scc1 .LBB0_733
	s_branch .LBB0_735

.LBB0_737:
	v_add_u32_e32 v234, 12, v0
	v_cndmask_b32_e64 v230, v234, v2, vcc
	v_max_i32_e32 v214, 0, v230
	v_lshl_add_u32 v214, v214, 9, v89
	v_add_u32_e32 v235, 8, v0
	v_add_u32_e32 v239, 4, v2
	v_cndmask_b32_e64 v231, v235, v239, vcc
	v_max_i32_e32 v218, 0, v231
	v_lshl_add_u32 v218, v218, 9, v89
	v_add_u32_e32 v236, 4, v0
	v_add_u32_e32 v240, 8, v2
	v_cndmask_b32_e64 v232, v236, v240, vcc
	v_max_i32_e32 v222, 0, v232
	v_lshl_add_u32 v222, v222, 9, v89
	v_add_u32_e32 v241, 12, v2
	v_cndmask_b32_e64 v233, v0, v241, vcc
	v_max_i32_e32 v226, 0, v233
	v_lshl_add_u32 v226, v226, 9, v89
	v_cmp_lt_i32_e64 s[98:99], -1, v230
	v_cmp_lt_i32_e64 s[100:101], -1, v231
	v_cmp_lt_i32_e64 s[38:39], -1, v232
	v_cndmask_b32_e64 v214, v246, v214, s[98:99]
	v_cmp_lt_i32_e64 s[98:99], -1, v233
	v_cndmask_b32_e64 v218, v246, v218, s[100:101]
	v_cndmask_b32_e64 v222, v246, v222, s[38:39]
	s_nop 0
	v_cndmask_b32_e64 v226, v246, v226, s[98:99]
	ds_read_b128 v[214:217], v214 offset:4096
	ds_read_b128 v[218:221], v218 offset:4096
	ds_read_b128 v[222:225], v222 offset:4096
	ds_read_b128 v[226:229], v226 offset:4096
	ds_read_b128 v[52:55], v3
	v_add_u32_e32 v0, 2, v0
	v_add_u32_e32 v2, -2, v2
	v_add_u32_e32 v3, 64, v3
	s_add_i32 s3, s3, 1
	s_cmp_lt_i32 s3, s2
	s_waitcnt lgkmcnt(0)
	v_mfma_f32_16x16x32_bf16 v[16:19], v[214:217], v[52:55], v[16:19]
	v_mfma_f32_16x16x32_bf16 v[12:15], v[218:221], v[52:55], v[12:15]
	v_mfma_f32_16x16x32_bf16 v[8:11], v[222:225], v[52:55], v[8:11]
	v_mfma_f32_16x16x32_bf16 v[4:7], v[226:229], v[52:55], v[4:7]
	s_cbranch_scc1 .LBB0_737

.LBB0_740:
	v_add_u32_e32 v234, 12, v0
	v_add_u32_e32 v238, -12, v2
	v_cndmask_b32_e64 v230, v234, v238, vcc
	v_max_i32_e32 v214, 0, v230
	v_lshl_add_u32 v214, v214, 9, v89
	v_add_u32_e32 v235, 8, v0
	v_add_u32_e32 v239, -8, v2
	v_cndmask_b32_e64 v231, v235, v239, vcc
	v_max_i32_e32 v218, 0, v231
	v_lshl_add_u32 v218, v218, 9, v89
	v_add_u32_e32 v236, 4, v0
	v_add_u32_e32 v240, -4, v2
	v_cndmask_b32_e64 v232, v236, v240, vcc
	v_max_i32_e32 v222, 0, v232
	v_lshl_add_u32 v222, v222, 9, v89
	v_cndmask_b32_e64 v233, v0, v2, vcc
	v_max_i32_e32 v226, 0, v233
	v_lshl_add_u32 v226, v226, 9, v89
	v_cmp_lt_i32_e64 s[98:99], -1, v230
	v_cmp_lt_i32_e64 s[100:101], -1, v231
	v_cmp_lt_i32_e64 s[38:39], -1, v232
	v_cndmask_b32_e64 v214, v246, v214, s[98:99]
	v_cmp_lt_i32_e64 s[98:99], -1, v233
	v_cndmask_b32_e64 v218, v246, v218, s[100:101]
	v_cndmask_b32_e64 v222, v246, v222, s[38:39]
	s_nop 0
	v_cndmask_b32_e64 v226, v246, v226, s[98:99]
	ds_read_b128 v[214:217], v214 offset:4096
	ds_read_b128 v[218:221], v218 offset:4096
	ds_read_b128 v[222:225], v222 offset:4096
	ds_read_b128 v[226:229], v226 offset:4096
	ds_read_b128 v[52:55], v3
	v_add_u32_e32 v0, 2, v0
	v_add_u32_e32 v2, -2, v2
	v_add_u32_e32 v3, 64, v3
	s_add_i32 s3, s3, 1
	s_cmp_lt_i32 s3, s2
	s_waitcnt lgkmcnt(0)
	v_mfma_f32_16x16x32_bf16 v[32:35], v[214:217], v[52:55], v[32:35]
	v_mfma_f32_16x16x32_bf16 v[28:31], v[218:221], v[52:55], v[28:31]
	v_mfma_f32_16x16x32_bf16 v[24:27], v[222:225], v[52:55], v[24:27]
	v_mfma_f32_16x16x32_bf16 v[20:23], v[226:229], v[52:55], v[20:23]
	s_cbranch_scc1 .LBB0_740

.LBB0_743:
	v_add_u32_e32 v234, 12, v0
	v_add_u32_e32 v238, -12, v2
	v_cndmask_b32_e64 v230, v234, v238, vcc
	v_max_i32_e32 v214, 0, v230
	v_lshl_add_u32 v214, v214, 9, v89
	v_add_u32_e32 v235, 8, v0
	v_add_u32_e32 v239, -8, v2
	v_cndmask_b32_e64 v231, v235, v239, vcc
	v_max_i32_e32 v218, 0, v231
	v_lshl_add_u32 v218, v218, 9, v89
	v_add_u32_e32 v236, 4, v0
	v_add_u32_e32 v240, -4, v2
	v_cndmask_b32_e64 v232, v236, v240, vcc
	v_max_i32_e32 v222, 0, v232
	v_lshl_add_u32 v222, v222, 9, v89
	v_cndmask_b32_e64 v233, v0, v2, vcc
	v_max_i32_e32 v226, 0, v233
	v_lshl_add_u32 v226, v226, 9, v89
	v_cmp_lt_i32_e64 s[98:99], -1, v230
	v_cmp_lt_i32_e64 s[100:101], -1, v231
	v_cmp_lt_i32_e64 s[38:39], -1, v232
	v_cndmask_b32_e64 v214, v246, v214, s[98:99]
	v_cmp_lt_i32_e64 s[98:99], -1, v233
	v_cndmask_b32_e64 v218, v246, v218, s[100:101]
	v_cndmask_b32_e64 v222, v246, v222, s[38:39]
	s_nop 0
	v_cndmask_b32_e64 v226, v246, v226, s[98:99]
	ds_read_b128 v[214:217], v214 offset:4096
	ds_read_b128 v[218:221], v218 offset:4096
	ds_read_b128 v[222:225], v222 offset:4096
	ds_read_b128 v[226:229], v226 offset:4096
	ds_read_b128 v[52:55], v3
	v_add_u32_e32 v0, 2, v0
	v_add_u32_e32 v2, -2, v2
	v_add_u32_e32 v3, 64, v3
	s_add_i32 s3, s3, 1
	s_cmp_lt_i32 s3, s2
	s_waitcnt lgkmcnt(0)
	v_mfma_f32_16x16x32_bf16 v[48:51], v[214:217], v[52:55], v[48:51]
	v_mfma_f32_16x16x32_bf16 v[44:47], v[218:221], v[52:55], v[44:47]
	v_mfma_f32_16x16x32_bf16 v[40:43], v[222:225], v[52:55], v[40:43]
	v_mfma_f32_16x16x32_bf16 v[36:39], v[226:229], v[52:55], v[36:39]
	s_cbranch_scc1 .LBB0_743

.LBB0_746:
	v_add_u32_e32 v234, 12, v103
	v_add_u32_e32 v238, -12, v101
	v_cndmask_b32_e64 v230, v234, v238, vcc
	v_max_i32_e32 v214, 0, v230
	v_lshl_add_u32 v214, v214, 9, v89
	v_add_u32_e32 v235, 8, v103
	v_add_u32_e32 v239, -8, v101
	v_cndmask_b32_e64 v231, v235, v239, vcc
	v_max_i32_e32 v218, 0, v231
	v_lshl_add_u32 v218, v218, 9, v89
	v_add_u32_e32 v236, 4, v103
	v_add_u32_e32 v240, -4, v101
	v_cndmask_b32_e64 v232, v236, v240, vcc
	v_max_i32_e32 v222, 0, v232
	v_lshl_add_u32 v222, v222, 9, v89
	v_cndmask_b32_e64 v233, v103, v101, vcc
	v_max_i32_e32 v226, 0, v233
	v_lshl_add_u32 v226, v226, 9, v89
	v_cmp_lt_i32_e64 s[98:99], -1, v230
	v_cmp_lt_i32_e64 s[100:101], -1, v231
	v_cmp_lt_i32_e64 s[38:39], -1, v232
	v_cndmask_b32_e64 v214, v246, v214, s[98:99]
	v_cmp_lt_i32_e64 s[98:99], -1, v233
	v_cndmask_b32_e64 v218, v246, v218, s[100:101]
	v_cndmask_b32_e64 v222, v246, v222, s[38:39]
	s_nop 0
	v_cndmask_b32_e64 v226, v246, v226, s[98:99]
	ds_read_b128 v[214:217], v214 offset:4096
	ds_read_b128 v[218:221], v218 offset:4096
	ds_read_b128 v[222:225], v222 offset:4096
	ds_read_b128 v[226:229], v226 offset:4096
	ds_read_b128 v[84:87], v91
	v_add_u32_e32 v103, 2, v103
	v_add_u32_e32 v101, -2, v101
	v_add_u32_e32 v91, 64, v91
	s_add_i32 s3, s3, 1
	s_cmp_lt_i32 s3, s2
	s_waitcnt lgkmcnt(0)
	v_mfma_f32_16x16x32_bf16 v[64:67], v[214:217], v[84:87], v[64:67]
	v_mfma_f32_16x16x32_bf16 v[60:63], v[218:221], v[84:87], v[60:63]
	v_mfma_f32_16x16x32_bf16 v[56:59], v[222:225], v[84:87], v[56:59]
	v_mfma_f32_16x16x32_bf16 v[52:55], v[226:229], v[84:87], v[52:55]
	s_cbranch_scc1 .LBB0_746
	s_mov_b64 s[38:39], 0
